# GLA-G1 chunk-state tiles: unrolled with scalar index arithmetic, operand reads issued ahead, scalar-base stores
# speedup vs baseline: 1.0047x; 1.0047x over previous
; #define LAS __attribute__((address_space(3)))
; __device__ __forceinline__ f32x4 mfma16(bf16x8 a, bf16x8 b, f32x4 c) { return __builtin_amdgcn_mfma_f32_16x16x32_bf16(a, b, c, 0, 0, 0); }
; __device__ __forceinline__ void gla_g1_item(int wv, const Params& p, int l, int it, LAS unsigned char* lds) {
;     ...
;     for (int tl = wave; tl < 36; tl += 8) { const int dir = tl / 18, r2 = tl % 18, mi = r2 / 3, ni = r2 % 3;
;         f32x4 acc = (f32x4){0.f, 0.f, 0.f, 0.f};
; #pragma unroll
;         for (int kk = 0; kk < 2; ++kk) {
;             const bf16x8 a = *(const LAS bf16x8*)(lds + GL_VT + (mi * 16 + fr) * 144 + kk * 64 + fq * 16);
;             const bf16x8 bb = *(const LAS bf16x8*)(lds + GL_X + (dir * 48 + ni * 16 + fr) * 144 + kk * 64 + fq * 16);
;             acc = mfma16(a, bb, acc); }
.LBB0_706:
	v_readfirstlane_b32 s5, v42
	v_mad_u32_u24 v81, v43, s55, v2
	v_mad_u32_u24 v82, v43, s55, v0
	v_mul_u32_u24_e32 v101, 0x60, v19
	v_lshl_add_u32 v83, v43, 1, v101
	s_mov_b32 s16, s5
	s_cmp_ge_u32 s16, 18
	s_cselect_b32 s17, 1, 0
	s_mul_i32 s18, s17, 18
	s_sub_i32 s16, s16, s18
	s_mul_i32 s18, s16, 11
	s_lshr_b32 s18, s18, 5
	s_mul_i32 s19, s18, 3
	s_sub_i32 s16, s16, s19
	s_mul_i32 s19, s18, 0x900
	v_add_u32_e32 v101, s19, v81
	s_mul_i32 s19, s17, 0x1b00
	s_mul_i32 s20, s16, 0x900
	s_add_i32 s19, s19, s20
	v_add_u32_e32 v102, s19, v82
	ds_read_b128 v[84:87], v101
	ds_read_b128 v[116:119], v102
	ds_read_b128 v[112:115], v101 offset:64
	ds_read_b128 v[120:123], v102 offset:64
	s_add_i32 s16, s5, 8
	s_cmp_ge_u32 s16, 18
	s_cselect_b32 s17, 1, 0
	s_mul_i32 s18, s17, 18
	s_sub_i32 s16, s16, s18
	s_mul_i32 s18, s16, 11
	s_lshr_b32 s18, s18, 5
	s_mul_i32 s19, s18, 3
	s_sub_i32 s16, s16, s19
	s_mul_i32 s19, s18, 0x900
	v_add_u32_e32 v101, s19, v81
	s_mul_i32 s19, s17, 0x1b00
	s_mul_i32 s20, s16, 0x900
	s_add_i32 s19, s19, s20
	v_add_u32_e32 v102, s19, v82
	ds_read_b128 v[88:91], v101
	ds_read_b128 v[132:135], v102
	ds_read_b128 v[124:127], v101 offset:64
	ds_read_b128 v[136:139], v102 offset:64
	s_add_i32 s16, s5, 16
	s_cmp_ge_u32 s16, 18
	s_cselect_b32 s17, 1, 0
	s_mul_i32 s18, s17, 18
	s_sub_i32 s16, s16, s18
	s_mul_i32 s18, s16, 11
	s_lshr_b32 s18, s18, 5
	s_mul_i32 s19, s18, 3
	s_sub_i32 s16, s16, s19
	s_mul_i32 s19, s18, 0x900
	v_add_u32_e32 v101, s19, v81
	s_mul_i32 s19, s17, 0x1b00
	s_mul_i32 s20, s16, 0x900
	s_add_i32 s19, s19, s20
	v_add_u32_e32 v102, s19, v82
	ds_read_b128 v[92:95], v101
	ds_read_b128 v[144:147], v102
	ds_read_b128 v[140:143], v101 offset:64
	ds_read_b128 v[148:151], v102 offset:64
	s_waitcnt lgkmcnt(8)
	v_mfma_f32_16x16x32_bf16 v[84:87], v[84:87], v[116:119], 0
	v_mfma_f32_16x16x32_bf16 v[84:87], v[112:115], v[120:123], v[84:87]
	s_add_i32 s16, s5, 24
	s_cmp_ge_u32 s16, 18
	s_cselect_b32 s17, 1, 0
	s_mul_i32 s18, s17, 18
	s_sub_i32 s16, s16, s18
	s_mul_i32 s18, s16, 11
	s_lshr_b32 s18, s18, 5
	s_mul_i32 s19, s18, 3
	s_sub_i32 s16, s16, s19
	s_mul_i32 s19, s18, 0x900
	v_add_u32_e32 v101, s19, v81
	s_mul_i32 s19, s17, 0x1b00
	s_mul_i32 s20, s16, 0x900
	s_add_i32 s19, s19, s20
	v_add_u32_e32 v102, s19, v82
	ds_read_b128 v[96:99], v101
	ds_read_b128 v[116:119], v102
	ds_read_b128 v[112:115], v101 offset:64
	ds_read_b128 v[120:123], v102 offset:64
	s_waitcnt lgkmcnt(8)
	v_mfma_f32_16x16x32_bf16 v[88:91], v[88:91], v[132:135], 0
	v_mfma_f32_16x16x32_bf16 v[88:91], v[124:127], v[136:139], v[88:91]
	s_add_i32 s16, s5, 32
	s_min_u32 s16, s16, 35
	s_cmp_ge_u32 s16, 18
	s_cselect_b32 s17, 1, 0
	s_mul_i32 s18, s17, 18
	s_sub_i32 s16, s16, s18
	s_mul_i32 s18, s16, 11
	s_lshr_b32 s18, s18, 5
	s_mul_i32 s19, s18, 3
	s_sub_i32 s16, s16, s19
	s_mul_i32 s19, s18, 0x900
	v_add_u32_e32 v101, s19, v81
	s_mul_i32 s19, s17, 0x1b00
	s_mul_i32 s20, s16, 0x900
	s_add_i32 s19, s19, s20
	v_add_u32_e32 v102, s19, v82
	ds_read_b128 v[104:107], v101
	ds_read_b128 v[132:135], v102
	ds_read_b128 v[124:127], v101 offset:64
	ds_read_b128 v[136:139], v102 offset:64
	s_waitcnt lgkmcnt(8)
	v_mfma_f32_16x16x32_bf16 v[92:95], v[92:95], v[144:147], 0
	v_mfma_f32_16x16x32_bf16 v[92:95], v[140:143], v[148:151], v[92:95]
	s_waitcnt lgkmcnt(4)
	v_mfma_f32_16x16x32_bf16 v[96:99], v[96:99], v[116:119], 0
	v_mfma_f32_16x16x32_bf16 v[96:99], v[112:115], v[120:123], v[96:99]
	s_waitcnt lgkmcnt(0)
; #define LAS __attribute__((address_space(3)))
; __device__ __forceinline__ bf16_t f2bf(float f) { unsigned u = __float_as_uint(f); u += 0x7FFFu + ((u >> 16) & 1u); return (bf16_t)(u >> 16); }
; __device__ __forceinline__ f32x4 mfma16(bf16x8 a, bf16x8 b, f32x4 c) { return __builtin_amdgcn_mfma_f32_16x16x32_bf16(a, b, c, 0, 0, 0); }
; __device__ __forceinline__ void gla_g1_item(int wv, const Params& p, int l, int it, LAS unsigned char* lds) {
;     ...
;         for (int kk = 0; kk < 2; ++kk) {
;             const bf16x8 a = *(const LAS bf16x8*)(lds + GL_VT + (mi * 16 + fr) * 144 + kk * 64 + fq * 16);
;             const bf16x8 bb = *(const LAS bf16x8*)(lds + GL_X + (dir * 48 + ni * 16 + fr) * 144 + kk * 64 + fq * 16);
;             acc = mfma16(a, bb, acc); }
;         bf16_t* dst = Sb + ((size_t)((b * 4 + h) * 2 + dir) * 36 + n) * 4608;
; #pragma unroll
;         for (int i = 0; i < 4; ++i) dst[(mi * 16 + fq * 4 + i) * 48 + ni * 16 + fr] = f2bf(acc[i]); }
	v_mfma_f32_16x16x32_bf16 v[104:107], v[104:107], v[132:135], 0
	v_mfma_f32_16x16x32_bf16 v[104:107], v[124:127], v[136:139], v[104:107]
	s_mov_b32 s16, s5
	s_cmp_ge_u32 s16, 18
	s_cselect_b32 s17, 1, 0
	s_mul_i32 s18, s17, 18
	s_sub_i32 s16, s16, s18
	s_mul_i32 s18, s16, 11
	s_lshr_b32 s18, s18, 5
	s_mul_i32 s19, s18, 3
	s_sub_i32 s16, s16, s19
	s_add_i32 s17, s4, s17
	s_mul_i32 s17, s17, 36
	s_add_i32 s17, s17, s6
	s_mul_i32 s17, s17, s85
	s_mul_i32 s18, s18, 0x600
	s_lshl_b32 s16, s16, 5
	s_add_i32 s17, s17, s18
	s_add_i32 s17, s17, s16
	s_add_u32 s16, s8, s17
	s_addc_u32 s17, s9, 0
	v_bfe_u32 v103, v84, 16, 1
	v_add3_u32 v108, v84, v103, s54
	global_store_short_d16_hi v83, v108, s[16:17]
	v_bfe_u32 v110, v85, 16, 1
	v_add3_u32 v111, v85, v110, s54
	global_store_short_d16_hi v83, v111, s[16:17] offset:96
	v_bfe_u32 v103, v86, 16, 1
	v_add3_u32 v108, v86, v103, s54
	global_store_short_d16_hi v83, v108, s[16:17] offset:192
	v_bfe_u32 v110, v87, 16, 1
	v_add3_u32 v111, v87, v110, s54
	global_store_short_d16_hi v83, v111, s[16:17] offset:288
	s_add_i32 s16, s5, 8
	s_cmp_ge_u32 s16, 18
	s_cselect_b32 s17, 1, 0
	s_mul_i32 s18, s17, 18
	s_sub_i32 s16, s16, s18
	s_mul_i32 s18, s16, 11
	s_lshr_b32 s18, s18, 5
	s_mul_i32 s19, s18, 3
	s_sub_i32 s16, s16, s19
	s_add_i32 s17, s4, s17
	s_mul_i32 s17, s17, 36
	s_add_i32 s17, s17, s6
	s_mul_i32 s17, s17, s85
	s_mul_i32 s18, s18, 0x600
	s_lshl_b32 s16, s16, 5
	s_add_i32 s17, s17, s18
	s_add_i32 s17, s17, s16
	s_add_u32 s16, s8, s17
	s_addc_u32 s17, s9, 0
	v_bfe_u32 v103, v88, 16, 1
	v_add3_u32 v108, v88, v103, s54
	global_store_short_d16_hi v83, v108, s[16:17]
	v_bfe_u32 v110, v89, 16, 1
	v_add3_u32 v111, v89, v110, s54
	global_store_short_d16_hi v83, v111, s[16:17] offset:96
	v_bfe_u32 v103, v90, 16, 1
	v_add3_u32 v108, v90, v103, s54
	global_store_short_d16_hi v83, v108, s[16:17] offset:192
	v_bfe_u32 v110, v91, 16, 1
	v_add3_u32 v111, v91, v110, s54
	global_store_short_d16_hi v83, v111, s[16:17] offset:288
	s_add_i32 s16, s5, 16
	s_cmp_ge_u32 s16, 18
	s_cselect_b32 s17, 1, 0
	s_mul_i32 s18, s17, 18
	s_sub_i32 s16, s16, s18
	s_mul_i32 s18, s16, 11
	s_lshr_b32 s18, s18, 5
	s_mul_i32 s19, s18, 3
	s_sub_i32 s16, s16, s19
	s_add_i32 s17, s4, s17
	s_mul_i32 s17, s17, 36
	s_add_i32 s17, s17, s6
	s_mul_i32 s17, s17, s85
	s_mul_i32 s18, s18, 0x600
	s_lshl_b32 s16, s16, 5
	s_add_i32 s17, s17, s18
	s_add_i32 s17, s17, s16
	s_add_u32 s16, s8, s17
	s_addc_u32 s17, s9, 0
	v_bfe_u32 v103, v92, 16, 1
	v_add3_u32 v108, v92, v103, s54
	global_store_short_d16_hi v83, v108, s[16:17]
	v_bfe_u32 v110, v93, 16, 1
	v_add3_u32 v111, v93, v110, s54
	global_store_short_d16_hi v83, v111, s[16:17] offset:96
	v_bfe_u32 v103, v94, 16, 1
	v_add3_u32 v108, v94, v103, s54
	global_store_short_d16_hi v83, v108, s[16:17] offset:192
	v_bfe_u32 v110, v95, 16, 1
	v_add3_u32 v111, v95, v110, s54
	global_store_short_d16_hi v83, v111, s[16:17] offset:288
	s_add_i32 s16, s5, 24
	s_cmp_ge_u32 s16, 18
	s_cselect_b32 s17, 1, 0
	s_mul_i32 s18, s17, 18
	s_sub_i32 s16, s16, s18
	s_mul_i32 s18, s16, 11
	s_lshr_b32 s18, s18, 5
	s_mul_i32 s19, s18, 3
	s_sub_i32 s16, s16, s19
	s_add_i32 s17, s4, s17
	s_mul_i32 s17, s17, 36
	s_add_i32 s17, s17, s6
	s_mul_i32 s17, s17, s85
	s_mul_i32 s18, s18, 0x600
	s_lshl_b32 s16, s16, 5
	s_add_i32 s17, s17, s18
	s_add_i32 s17, s17, s16
	s_add_u32 s16, s8, s17
	s_addc_u32 s17, s9, 0
	v_bfe_u32 v103, v96, 16, 1
	v_add3_u32 v108, v96, v103, s54
	global_store_short_d16_hi v83, v108, s[16:17]
	v_bfe_u32 v110, v97, 16, 1
	v_add3_u32 v111, v97, v110, s54
	global_store_short_d16_hi v83, v111, s[16:17] offset:96
	v_bfe_u32 v103, v98, 16, 1
	v_add3_u32 v108, v98, v103, s54
	global_store_short_d16_hi v83, v108, s[16:17] offset:192
	v_bfe_u32 v110, v99, 16, 1
	v_add3_u32 v111, v99, v110, s54
	global_store_short_d16_hi v83, v111, s[16:17] offset:288
	s_cmp_lt_u32 s5, 4
	s_cbranch_scc0 .Lg1t_skip
	s_add_i32 s16, s5, 32
	s_min_u32 s16, s16, 35
	s_cmp_ge_u32 s16, 18
	s_cselect_b32 s17, 1, 0
	s_mul_i32 s18, s17, 18
	s_sub_i32 s16, s16, s18
	s_mul_i32 s18, s16, 11
	s_lshr_b32 s18, s18, 5
	s_mul_i32 s19, s18, 3
	s_sub_i32 s16, s16, s19
	s_add_i32 s17, s4, s17
	s_mul_i32 s17, s17, 36
	s_add_i32 s17, s17, s6
	s_mul_i32 s17, s17, s85
	s_mul_i32 s18, s18, 0x600
	s_lshl_b32 s16, s16, 5
	s_add_i32 s17, s17, s18
	s_add_i32 s17, s17, s16
	s_add_u32 s16, s8, s17
	s_addc_u32 s17, s9, 0
	v_bfe_u32 v103, v104, 16, 1
	v_add3_u32 v108, v104, v103, s54
	global_store_short_d16_hi v83, v108, s[16:17]
	v_bfe_u32 v110, v105, 16, 1
	v_add3_u32 v111, v105, v110, s54
	global_store_short_d16_hi v83, v111, s[16:17] offset:96
	v_bfe_u32 v103, v106, 16, 1
	v_add3_u32 v108, v106, v103, s54
	global_store_short_d16_hi v83, v108, s[16:17] offset:192
	v_bfe_u32 v110, v107, 16, 1
	v_add3_u32 v111, v107, v110, s54
	global_store_short_d16_hi v83, v111, s[16:17] offset:288
.Lg1t_skip:
.LBB0_707:
	s_or_b64 exec, exec, s[14:15]
	s_branch .LBB0_666
